# layer-1 MLP1 weight conversion: tiles 0..2175 done by workgroups 192.. during the cmp phase (fully idle there), the rest at the original place
# speedup vs baseline: 1.0049x; 1.0049x over previous
.LBB0_690:
	s_load_dwordx4 s[4:7], s[0:1], 0x78
	s_waitcnt lgkmcnt(0)
	v_writelane_b32 v232, s4, 21
	v_writelane_b32 v232, s5, 22
	v_writelane_b32 v232, s6, 23
	v_writelane_b32 v232, s7, 24
	v_mov_b32_e32 v0, v136
	s_and_b64 vcc, exec, s[10:11]
	s_cbranch_vccnz .LBB0_702
	s_load_dwordx4 s[4:7], s[0:1], 0x78
	v_ashrrev_i32_e32 v9, 3, v0
	v_lshlrev_b32_e32 v0, 3, v0
	v_and_b32_e32 v8, 56, v0
	v_lshl_add_u32 v2, v9, 2, 16
	s_waitcnt lgkmcnt(0)
	s_add_u32 s16, s6, 0x4000000
	s_addc_u32 s17, s7, 0
	s_add_u32 s18, s4, 0x2000
	s_addc_u32 s19, s5, 0
	s_add_u32 s20, s52, 0x2800000
	s_addc_u32 s21, s53, 0
	s_cmp_lg_u64 s[4:5], 0
	s_cselect_b64 s[6:7], -1, 0
	s_movk_i32 s4, 0x104
	v_mul_u32_u24_e32 v3, 0x104, v8
	v_lshl_add_u32 v0, v8, 2, 16
	v_mul_lo_u32 v1, v9, s4
	v_cndmask_b32_e64 v4, 0, 1, s[6:7]
	v_add_u32_e32 v18, v2, v3
	v_mov_b32_e32 v11, 0
	s_add_i32 s4, s2, 0x880
	s_lshl_b32 s4, s4, 6
	s_lshl_b32 s5, s34, 6
	v_cmp_ne_u32_e64 s[14:15], 1, v4
	s_movk_i32 s6, 0x2000
	v_add_u32_e32 v13, v0, v1
	v_lshlrev_b32_e32 v10, 1, v8
	v_add_u32_e32 v19, 0x400, v18
	s_add_i32 s7, s2, 0x880
	s_branch .LBB0_693

.Lgate_skip:
	s_cmp_lt_u32 s2, 192
	s_cbranch_scc1 .Lmv1_skip
	s_sub_i32 s60, s2, 192
	s_sub_i32 s61, s34, 192
	v_mov_b32_e32 v0, v136
	v_readlane_b32 s4, v232, 21
	v_readlane_b32 s5, v232, 22
	v_readlane_b32 s6, v232, 23
	v_readlane_b32 s7, v232, 24
	s_nop 3
	v_ashrrev_i32_e32 v9, 3, v0
	v_lshlrev_b32_e32 v0, 3, v0
	v_and_b32_e32 v8, 56, v0
	v_lshl_add_u32 v2, v9, 2, 16
	s_waitcnt lgkmcnt(0)
	s_add_u32 s16, s6, 0x4000000
	s_addc_u32 s17, s7, 0
	s_add_u32 s18, s4, 0x2000
	s_addc_u32 s19, s5, 0
	s_add_u32 s20, s30, 0x2800000
	s_addc_u32 s21, s31, 0
	s_cmp_lg_u64 s[4:5], 0
	s_cselect_b64 s[6:7], -1, 0
	s_movk_i32 s4, 0x104
	v_mul_u32_u24_e32 v3, 0x104, v8
	v_lshl_add_u32 v0, v8, 2, 16
	v_mul_lo_u32 v1, v9, s4
	v_cndmask_b32_e64 v4, 0, 1, s[6:7]
	v_add_u32_e32 v18, v2, v3
	v_mov_b32_e32 v11, 0
	s_lshl_b32 s4, s60, 6
	s_lshl_b32 s5, s61, 6
	v_cmp_ne_u32_e64 s[14:15], 1, v4
	s_movk_i32 s6, 0x2000
	v_add_u32_e32 v13, v0, v1
	v_lshlrev_b32_e32 v10, 1, v8
	v_add_u32_e32 v19, 0x400, v18
	s_mov_b32 s7, s60
	s_branch .Lmv1_693
.Lmv1_692:
	s_or_b64 exec, exec, s[62:63]
	s_add_i32 s7, s7, s61
	s_add_i32 s4, s4, s5
	s_cmpk_lt_i32 s7, 0x880
	s_barrier
	s_cbranch_scc0 .Lmv1_done
